# retention: next-chunk global loads issued before the staging barrier (right after the ds_writes) instead of after it
# baseline (speedup 1.0000x reference)
.LBB0_438:
	s_waitcnt vmcnt(2)
	ds_write_b128 v176, v[2:5]
	ds_write_b128 v176, v[6:9] offset:33792
	ds_write_b128 v177, v[10:13]
	ds_write_b128 v177, v[14:17] offset:33792
	ds_write_b128 v178, v[18:21]
	ds_write_b128 v178, v[22:25] offset:33792
	ds_write_b128 v179, v[30:33]
	ds_write_b128 v179, v[34:37] offset:33792
	ds_write_b128 v180, v[26:29]
	v_lshlrev_b32_e32 v2, 16, v26
	v_and_b32_e32 v3, 0xffff0000, v26
	v_lshlrev_b32_e32 v4, 16, v27
	v_and_b32_e32 v5, 0xffff0000, v27
	v_pk_mul_f32 v[2:3], v[124:125], v[2:3]
	v_pk_mul_f32 v[4:5], v[124:125], v[4:5]
	v_cvt_pk_bf16_f32 v2, v2, v3
	v_cvt_pk_bf16_f32 v3, v4, v5
	v_lshlrev_b32_e32 v4, 16, v28
	v_and_b32_e32 v5, 0xffff0000, v28
	v_lshlrev_b32_e32 v6, 16, v29
	v_and_b32_e32 v7, 0xffff0000, v29
	v_pk_mul_f32 v[4:5], v[124:125], v[4:5]
	v_pk_mul_f32 v[6:7], v[124:125], v[6:7]
	v_cvt_pk_bf16_f32 v4, v4, v5
	v_cvt_pk_bf16_f32 v5, v6, v7
	v_lshl_add_u64 v[6:7], s[78:79], 0, v[122:123]
	ds_write_b128 v181, v[2:5]
	v_add_co_u32_e64 v2, s[36:37], s27, v6
	v_lshl_add_u64 v[14:15], s[78:79], 0, v[120:121]
	s_nop 0
	v_addc_co_u32_e64 v3, s[36:37], 0, v7, s[36:37]
	v_add_co_u32_e64 v6, s[36:37], s28, v6
	v_lshl_add_u64 v[22:23], s[78:79], 0, v[118:119]
	s_nop 0
	v_addc_co_u32_e64 v7, s[36:37], 0, v7, s[36:37]
	v_add_co_u32_e64 v10, s[36:37], s27, v14
	v_lshl_add_u64 v[26:27], s[78:79], 0, v[116:117]
	s_nop 0
	v_addc_co_u32_e64 v11, s[36:37], 0, v15, s[36:37]
	v_add_co_u32_e64 v14, s[36:37], s28, v14
	s_nop 0
	v_addc_co_u32_e64 v15, s[36:37], 0, v15, s[36:37]
	v_add_co_u32_e64 v18, s[36:37], s27, v22
	s_nop 0
	v_addc_co_u32_e64 v19, s[36:37], 0, v23, s[36:37]
	v_add_co_u32_e64 v22, s[36:37], s28, v22
	s_nop 1
	v_addc_co_u32_e64 v23, s[36:37], 0, v23, s[36:37]
	v_add_co_u32_e64 v28, s[36:37], s27, v26
	global_load_dwordx4 v[2:5], v[2:3], off
	s_nop 0
	v_addc_co_u32_e64 v29, s[36:37], 0, v27, s[36:37]
	v_add_co_u32_e64 v26, s[36:37], s28, v26
	global_load_dwordx4 v[30:33], v[28:29], off
	s_nop 0
	v_addc_co_u32_e64 v27, s[36:37], 0, v27, s[36:37]
	global_load_dwordx4 v[34:37], v[26:27], off
	v_lshl_add_u64 v[26:27], s[78:79], 0, v[114:115]
	global_load_dwordx4 v[6:9], v[6:7], off
	v_add_u32_e32 v205, v131, v127
	global_load_dwordx4 v[10:13], v[10:11], off
	s_mov_b32 s36, 0x59a00000
	global_load_dwordx4 v[14:17], v[14:15], off
	v_mov_b32_e32 v105, v104
	global_load_dwordx4 v[18:21], v[18:19], off
	v_pk_mul_f32 v[68:69], v[104:105], v[68:69]
	global_load_dwordx4 v[22:25], v[22:23], off
	v_pk_mul_f32 v[66:67], v[106:107], v[66:67]
	global_load_dwordx4 v[26:29], v[26:27], off
	s_waitcnt lgkmcnt(0)
	s_barrier
	ds_read_b128 v[70:73], v182
	ds_read_b128 v[74:77], v183 offset:33792
	ds_read_b128 v[188:191], v183 offset:42240
	s_waitcnt lgkmcnt(1)
	v_mfma_f32_16x16x32_bf16 v[74:77], v[70:73], v[74:77], 0
	v_mul_f32_e64 v64, v104, v64
	v_mul_f32_e64 v65, v105, v65
	v_pk_mul_f32 v[62:63], v[106:107], v[62:63]
	v_pk_mul_f32 v[60:61], v[104:105], v[60:61]
	s_waitcnt lgkmcnt(0)
	v_mfma_f32_16x16x32_bf16 v[70:73], v[70:73], v[188:191], 0
	ds_read_b128 v[188:191], v182 offset:64
	ds_read_b128 v[192:195], v183 offset:33856
	ds_read_b128 v[206:209], v183 offset:42304
	v_pk_mul_f32 v[58:59], v[106:107], v[58:59]
	v_pk_mul_f32 v[48:49], v[104:105], v[48:49]
	s_waitcnt lgkmcnt(1)
	v_mfma_f32_16x16x32_bf16 v[74:77], v[188:191], v[192:195], v[74:77]
	v_mul_f32_e64 v46, v106, v46
	v_mul_f32_e64 v47, v107, v47
	v_pk_mul_f32 v[44:45], v[104:105], v[44:45]
	v_pk_mul_f32 v[42:43], v[106:107], v[42:43]
	s_waitcnt lgkmcnt(0)
	v_mfma_f32_16x16x32_bf16 v[70:73], v[188:191], v[206:209], v[70:73]
	ds_read_b128 v[188:191], v182 offset:128
	ds_read_b128 v[192:195], v183 offset:33920
	ds_read_b128 v[206:209], v183 offset:42368
	v_pk_mul_f32 v[40:41], v[104:105], v[40:41]
	v_pk_mul_f32 v[38:39], v[106:107], v[38:39]
	s_waitcnt lgkmcnt(1)
	v_mfma_f32_16x16x32_bf16 v[74:77], v[188:191], v[192:195], v[74:77]
	s_add_i32 s39, s39, -1
	v_lshl_add_u64 v[114:115], v[114:115], 0, s[34:35]
	v_lshl_add_u64 v[116:117], v[116:117], 0, s[86:87]
	s_waitcnt lgkmcnt(0)
	v_mfma_f32_16x16x32_bf16 v[70:73], v[188:191], v[206:209], v[70:73]
	ds_read_b128 v[188:191], v182 offset:192
	ds_read_b128 v[192:195], v183 offset:33984
	ds_read_b128 v[206:209], v183 offset:42432
	v_lshl_add_u64 v[118:119], v[118:119], 0, s[86:87]
	v_lshl_add_u64 v[120:121], v[120:121], 0, s[86:87]
	s_waitcnt lgkmcnt(1)
	v_mfma_f32_16x16x32_bf16 v[74:77], v[188:191], v[192:195], v[74:77]
	v_lshl_add_u64 v[122:123], v[122:123], 0, s[86:87]
	s_cmp_lg_u32 s39, 0
	s_waitcnt lgkmcnt(0)
	v_mfma_f32_16x16x32_bf16 v[70:73], v[188:191], v[206:209], v[70:73]
	ds_read_b128 v[188:191], v182 offset:256
	ds_read_b128 v[192:195], v183 offset:34048
	ds_read_b128 v[206:209], v183 offset:42496
	s_waitcnt lgkmcnt(1)
	v_mfma_f32_16x16x32_bf16 v[74:77], v[188:191], v[192:195], v[74:77]
	s_waitcnt lgkmcnt(0)
	v_mfma_f32_16x16x32_bf16 v[70:73], v[188:191], v[206:209], v[70:73]
	ds_read_b128 v[188:191], v182 offset:320
	ds_read_b128 v[192:195], v183 offset:34112
	ds_read_b128 v[206:209], v183 offset:42560
	s_waitcnt lgkmcnt(1)
	v_mfma_f32_16x16x32_bf16 v[74:77], v[188:191], v[192:195], v[74:77]
	s_waitcnt lgkmcnt(0)
	v_mfma_f32_16x16x32_bf16 v[70:73], v[188:191], v[206:209], v[70:73]
	ds_read_b128 v[188:191], v182 offset:384
	ds_read_b128 v[192:195], v183 offset:34176
	ds_read_b128 v[206:209], v183 offset:42624
	s_waitcnt lgkmcnt(1)
	v_mfma_f32_16x16x32_bf16 v[74:77], v[188:191], v[192:195], v[74:77]
	s_waitcnt lgkmcnt(0)
	v_mfma_f32_16x16x32_bf16 v[70:73], v[188:191], v[206:209], v[70:73]
	ds_read_b128 v[188:191], v182 offset:448
	ds_read_b128 v[192:195], v183 offset:34240
	ds_read_b128 v[206:209], v183 offset:42688
	s_waitcnt lgkmcnt(1)
	v_mfma_f32_16x16x32_bf16 v[74:77], v[188:191], v[192:195], v[74:77]
	s_waitcnt lgkmcnt(0)
	v_mfma_f32_16x16x32_bf16 v[70:73], v[188:191], v[206:209], v[70:73]
	s_nop 5
	v_mul_f32_e32 v1, v103, v74
	v_cvt_pk_bf16_f32 v1, v1, s0
	v_add_u32_e32 v74, v131, v126
	ds_write_b16 v74, v1
	v_add_u32_e32 v206, v134, v127
	v_mul_f32_e32 v1, v198, v70
	v_cvt_pk_bf16_f32 v1, v1, s0
	ds_write_b16 v205, v1
	v_mul_f32_e32 v1, v199, v75
	v_cvt_pk_bf16_f32 v1, v1, s0
	v_add_u32_e32 v75, v134, v126
	ds_write_b16 v75, v1
	v_mul_f32_e32 v1, v200, v71
	v_cvt_pk_bf16_f32 v1, v1, s0
	ds_write_b16 v206, v1
	v_mul_f32_e32 v1, v201, v76
	v_cvt_pk_bf16_f32 v1, v1, s0
	v_add_u32_e32 v76, v137, v126
	ds_write_b16 v76, v1
	v_mul_f32_e32 v1, v202, v72
	v_cvt_pk_bf16_f32 v1, v1, s0
	v_add_u32_e32 v207, v137, v127
	ds_write_b16 v207, v1
	v_mul_f32_e32 v1, v203, v77
	v_cvt_pk_bf16_f32 v1, v1, s0
	v_add_u32_e32 v77, v140, v126
	ds_write_b16 v77, v1
	v_mul_f32_e32 v1, v204, v73
	v_cvt_pk_bf16_f32 v1, v1, s0
	v_add_u32_e32 v208, v140, v127
	ds_write_b16 v208, v1
	s_waitcnt lgkmcnt(0)
	s_barrier
	ds_read_b128 v[70:73], v182
	ds_read_b128 v[188:191], v184
	ds_read_b128 v[192:195], v184 offset:8448
	s_waitcnt lgkmcnt(1)
	v_mfma_f32_16x16x32_bf16 v[188:191], v[188:191], v[70:73], 0
	s_waitcnt lgkmcnt(0)
	v_mfma_f32_16x16x32_bf16 v[70:73], v[192:195], v[70:73], 0
	ds_read_b128 v[192:195], v182 offset:64
	ds_read_b128 v[210:213], v184 offset:64
	ds_read_b128 v[214:217], v184 offset:8512
	s_waitcnt lgkmcnt(1)
	v_mfma_f32_16x16x32_bf16 v[188:191], v[210:213], v[192:195], v[188:191]
	s_waitcnt lgkmcnt(0)
	v_mfma_f32_16x16x32_bf16 v[70:73], v[214:217], v[192:195], v[70:73]
	ds_read_b128 v[192:195], v182 offset:128
	ds_read_b128 v[210:213], v184 offset:128
	ds_read_b128 v[214:217], v184 offset:8576
	s_waitcnt lgkmcnt(1)
	v_mfma_f32_16x16x32_bf16 v[188:191], v[210:213], v[192:195], v[188:191]
	s_waitcnt lgkmcnt(0)
	v_mfma_f32_16x16x32_bf16 v[70:73], v[214:217], v[192:195], v[70:73]
	ds_read_b128 v[192:195], v182 offset:192
	ds_read_b128 v[210:213], v184 offset:192
	ds_read_b128 v[214:217], v184 offset:8640
	s_waitcnt lgkmcnt(1)
	v_mfma_f32_16x16x32_bf16 v[188:191], v[210:213], v[192:195], v[188:191]
	s_waitcnt lgkmcnt(0)
	v_mfma_f32_16x16x32_bf16 v[70:73], v[214:217], v[192:195], v[70:73]
	ds_read_b128 v[192:195], v182 offset:256
	ds_read_b128 v[210:213], v184 offset:256
	ds_read_b128 v[214:217], v184 offset:8704
	s_waitcnt lgkmcnt(1)
	v_mfma_f32_16x16x32_bf16 v[188:191], v[210:213], v[192:195], v[188:191]
	s_waitcnt lgkmcnt(0)
	v_mfma_f32_16x16x32_bf16 v[70:73], v[214:217], v[192:195], v[70:73]
	ds_read_b128 v[192:195], v182 offset:320
	ds_read_b128 v[210:213], v184 offset:320
	ds_read_b128 v[214:217], v184 offset:8768
	s_waitcnt lgkmcnt(1)
	v_mfma_f32_16x16x32_bf16 v[188:191], v[210:213], v[192:195], v[188:191]
	s_waitcnt lgkmcnt(0)
	v_mfma_f32_16x16x32_bf16 v[70:73], v[214:217], v[192:195], v[70:73]
	ds_read_b128 v[192:195], v182 offset:384
	ds_read_b128 v[210:213], v184 offset:384
	ds_read_b128 v[214:217], v184 offset:8832
	s_waitcnt lgkmcnt(1)
	v_mfma_f32_16x16x32_bf16 v[188:191], v[210:213], v[192:195], v[188:191]
	s_waitcnt lgkmcnt(0)
	v_mfma_f32_16x16x32_bf16 v[70:73], v[214:217], v[192:195], v[70:73]
	ds_read_b128 v[192:195], v182 offset:448
	ds_read_b128 v[210:213], v184 offset:448
	ds_read_b128 v[214:217], v184 offset:8896
	s_waitcnt lgkmcnt(1)
	v_mfma_f32_16x16x32_bf16 v[188:191], v[210:213], v[192:195], v[188:191]
	s_waitcnt lgkmcnt(0)
	v_mfma_f32_16x16x32_bf16 v[70:73], v[214:217], v[192:195], v[70:73]
	ds_read_b128 v[192:195], v185
	s_nop 4
	v_pk_mul_f32 v[190:191], v[110:111], v[190:191]
	v_pk_mul_f32 v[188:189], v[108:109], v[188:189]
	ds_read_b64_tr_b16 v[214:215], v141
	ds_read_b64_tr_b16 v[216:217], v142
	ds_read_b64_tr_b16 v[210:211], v143
	ds_read_b64_tr_b16 v[212:213], v144
	s_waitcnt lgkmcnt(0)
	s_waitcnt lgkmcnt(0)
	s_nop 0
	v_mfma_f32_16x16x32_bf16 v[188:191], v[214:217], v[192:195], v[188:191]
	v_mul_f32_e64 v72, v110, v72
	v_mul_f32_e64 v73, v111, v73
	v_pk_mul_f32 v[70:71], v[108:109], v[70:71]
	s_nop 1
	v_mfma_f32_16x16x32_bf16 v[70:73], v[210:213], v[192:195], v[70:73]
	ds_read_b128 v[192:195], v185 offset:64
	ds_read_b64_tr_b16 v[214:215], v145
	ds_read_b64_tr_b16 v[216:217], v146
	ds_read_b64_tr_b16 v[210:211], v147
	ds_read_b64_tr_b16 v[212:213], v148
	s_waitcnt lgkmcnt(0)
	s_waitcnt lgkmcnt(0)
	v_mfma_f32_16x16x32_bf16 v[188:191], v[214:217], v[192:195], v[188:191]
	v_mfma_f32_16x16x32_bf16 v[192:195], v[210:213], v[192:195], v[70:73]
	s_nop 6
	v_cvt_pk_bf16_f32 v70, v188, v189
	v_lshl_add_u64 v[188:189], s[78:79], 0, v[112:113]
	v_add_co_u32_e64 v188, s[36:37], s36, v188
	v_cvt_pk_bf16_f32 v71, v190, v191
	s_nop 0
	v_addc_co_u32_e64 v189, s[36:37], 0, v189, s[36:37]
	v_cvt_pk_bf16_f32 v72, v192, v193
	v_cvt_pk_bf16_f32 v73, v194, v195
	global_store_dwordx2 v[188:189], v[70:71], off
	global_store_dwordx2 v[188:189], v[72:73], off offset:32
	v_pk_mul_f32 v[72:73], v[104:105], v[52:53]
	v_pk_mul_f32 v[70:71], v[106:107], v[50:51]
	v_pk_mul_f32 v[52:53], v[104:105], v[56:57]
	v_pk_mul_f32 v[50:51], v[106:107], v[54:55]
	ds_read_b64_tr_b16 v[188:189], v149
	ds_read_b64_tr_b16 v[190:191], v151
	ds_read_b64_tr_b16 v[54:55], v152
	ds_read_b64_tr_b16 v[56:57], v153
	s_waitcnt lgkmcnt(0)
	ds_read_b64_tr_b16 v[210:211], v150
	ds_read_b64_tr_b16 v[212:213], v154
	ds_read_b64_tr_b16 v[192:193], v155
	ds_read_b64_tr_b16 v[194:195], v156
	s_waitcnt lgkmcnt(0)
	ds_read_b64_tr_b16 v[218:219], v157
	ds_read_b64_tr_b16 v[220:221], v158
	ds_read_b64_tr_b16 v[214:215], v159
	ds_read_b64_tr_b16 v[216:217], v160
	s_waitcnt lgkmcnt(0)
	v_lshl_add_u64 v[112:113], v[112:113], 0, s[34:35]
	v_mfma_f32_16x16x32_bf16 v[66:69], v[188:191], v[210:213], v[66:69]
	v_mfma_f32_16x16x32_bf16 v[62:65], v[188:191], v[192:195], v[62:65]
	v_mfma_f32_16x16x32_bf16 v[58:61], v[188:191], v[218:221], v[58:61]
	v_mfma_f32_16x16x32_bf16 v[70:73], v[188:191], v[214:217], v[70:73]
	v_mfma_f32_16x16x32_bf16 v[188:191], v[54:57], v[210:213], v[50:53]
	v_mfma_f32_16x16x32_bf16 v[46:49], v[54:57], v[192:195], v[46:49]
	ds_read_b64_tr_b16 v[50:51], v161
	ds_read_b64_tr_b16 v[52:53], v163
	ds_read_b64_tr_b16 v[192:193], v164
	ds_read_b64_tr_b16 v[194:195], v165
	s_waitcnt lgkmcnt(0)
	v_mfma_f32_16x16x32_bf16 v[42:45], v[54:57], v[218:221], v[42:45]
	v_mfma_f32_16x16x32_bf16 v[38:41], v[54:57], v[214:217], v[38:41]
	ds_read_b64_tr_b16 v[54:55], v162
	ds_read_b64_tr_b16 v[56:57], v166
	ds_read_b64_tr_b16 v[210:211], v167
	ds_read_b64_tr_b16 v[212:213], v168
	s_waitcnt lgkmcnt(0)
	ds_read_b64_tr_b16 v[218:219], v169
	ds_read_b64_tr_b16 v[220:221], v170
	ds_read_b64_tr_b16 v[214:215], v171
	ds_read_b64_tr_b16 v[216:217], v172
	s_waitcnt lgkmcnt(0)
	s_nop 0
	v_mfma_f32_16x16x32_bf16 v[66:69], v[50:53], v[54:57], v[66:69]
	s_barrier
	v_mfma_f32_16x16x32_bf16 v[62:65], v[50:53], v[210:213], v[62:65]
	v_mfma_f32_16x16x32_bf16 v[58:61], v[50:53], v[218:221], v[58:61]
	v_mfma_f32_16x16x32_bf16 v[50:53], v[50:53], v[214:217], v[70:73]
	v_mfma_f32_16x16x32_bf16 v[54:57], v[192:195], v[54:57], v[188:191]
	s_nop 2
	v_cvt_pk_bf16_f32 v70, v66, v67
	v_cvt_pk_bf16_f32 v71, v68, v69
	ds_write_b64 v196, v[70:71]
	v_mfma_f32_16x16x32_bf16 v[46:49], v[192:195], v[210:213], v[46:49]
	v_cvt_pk_bf16_f32 v70, v62, v63
	v_cvt_pk_bf16_f32 v71, v64, v65
	ds_write_b64 v196, v[70:71] offset:8448
	v_mfma_f32_16x16x32_bf16 v[42:45], v[192:195], v[218:221], v[42:45]
	v_cvt_pk_bf16_f32 v70, v58, v59
	v_cvt_pk_bf16_f32 v71, v60, v61
	ds_write_b64 v196, v[70:71] offset:16896
	v_mfma_f32_16x16x32_bf16 v[38:41], v[192:195], v[214:217], v[38:41]
	v_cvt_pk_bf16_f32 v70, v50, v51
	v_cvt_pk_bf16_f32 v71, v52, v53
	ds_write_b64 v196, v[70:71] offset:25344
	v_cvt_pk_bf16_f32 v70, v54, v55
	v_cvt_pk_bf16_f32 v71, v56, v57
	ds_write_b64 v197, v[70:71]
	v_cvt_pk_bf16_f32 v70, v46, v47
	v_cvt_pk_bf16_f32 v71, v48, v49
	ds_write_b64 v197, v[70:71] offset:8448
	v_cvt_pk_bf16_f32 v70, v42, v43
	v_cvt_pk_bf16_f32 v71, v44, v45
	ds_write_b64 v197, v[70:71] offset:16896
	v_cvt_pk_bf16_f32 v70, v38, v39
	v_cvt_pk_bf16_f32 v71, v40, v41
	ds_write_b64 v197, v[70:71] offset:25344
	s_cbranch_scc1 .LBB0_438
	s_waitcnt vmcnt(10)
	ds_write_b128 v176, v[2:5]
	s_waitcnt vmcnt(7)
	ds_write_b128 v176, v[6:9] offset:33792
	s_waitcnt vmcnt(6)
	ds_write_b128 v177, v[10:13]
	s_waitcnt vmcnt(5)
	ds_write_b128 v177, v[14:17] offset:33792
	s_waitcnt vmcnt(4)
	ds_write_b128 v178, v[18:21]
	s_waitcnt vmcnt(3)
	ds_write_b128 v178, v[22:25] offset:33792
	ds_write_b128 v179, v[30:33]
	ds_write_b128 v179, v[34:37] offset:33792
	s_waitcnt vmcnt(2)
	ds_write_b128 v180, v[26:29]
	v_lshlrev_b32_e32 v2, 16, v26
	v_and_b32_e32 v3, 0xffff0000, v26
	v_lshlrev_b32_e32 v4, 16, v27
	v_and_b32_e32 v5, 0xffff0000, v27
	v_pk_mul_f32 v[2:3], v[124:125], v[2:3]
	v_pk_mul_f32 v[4:5], v[124:125], v[4:5]
	v_cvt_pk_bf16_f32 v2, v2, v3
	v_cvt_pk_bf16_f32 v3, v4, v5
	v_lshlrev_b32_e32 v4, 16, v28
	v_and_b32_e32 v5, 0xffff0000, v28
	v_lshlrev_b32_e32 v6, 16, v29
	v_and_b32_e32 v7, 0xffff0000, v29
	v_pk_mul_f32 v[4:5], v[124:125], v[4:5]
	v_pk_mul_f32 v[6:7], v[124:125], v[6:7]
	v_cvt_pk_bf16_f32 v4, v4, v5
	v_cvt_pk_bf16_f32 v5, v6, v7
	ds_write_b128 v181, v[2:5]
	s_waitcnt lgkmcnt(0)
	s_barrier
	ds_read_b128 v[2:5], v182
	ds_read_b128 v[6:9], v183 offset:33792
	ds_read_b128 v[10:13], v182 offset:64
	ds_read_b128 v[14:17], v183 offset:33856
	s_waitcnt lgkmcnt(2)
	v_mfma_f32_16x16x32_bf16 v[6:9], v[2:5], v[6:9], 0
	ds_read_b128 v[18:21], v183 offset:42240
	ds_read_b128 v[22:25], v183 offset:42304
	s_lshl_b32 s15, s15, 1
	s_add_u32 s15, s7, s15
	s_waitcnt lgkmcnt(2)
	v_mfma_f32_16x16x32_bf16 v[6:9], v[10:13], v[14:17], v[6:9]
	ds_read_b128 v[14:17], v182 offset:128
	s_addc_u32 s39, s10, 0
	s_lshl_b64 s[36:37], s[40:41], 1
	s_waitcnt lgkmcnt(2)
	v_mfma_f32_16x16x32_bf16 v[2:5], v[2:5], v[18:21], 0
	s_add_u32 s36, s15, s36
	s_addc_u32 s37, s39, s37
	v_pk_mul_f32 v[30:31], v[104:105], v[60:61]
	s_waitcnt lgkmcnt(1)
	v_mfma_f32_16x16x32_bf16 v[2:5], v[10:13], v[22:25], v[2:5]
	ds_read_b128 v[10:13], v183 offset:33920
	ds_read_b128 v[18:21], v182 offset:192
	ds_read_b128 v[22:25], v183 offset:33984
	v_pk_mul_f32 v[52:53], v[104:105], v[52:53]
	v_pk_mul_f32 v[50:51], v[106:107], v[50:51]
	s_waitcnt lgkmcnt(2)
	v_mfma_f32_16x16x32_bf16 v[6:9], v[14:17], v[10:13], v[6:9]
	ds_read_b128 v[10:13], v183 offset:42368
	ds_read_b128 v[26:29], v183 offset:42432
	v_pk_mul_f32 v[48:49], v[104:105], v[48:49]
	v_pk_mul_f32 v[46:47], v[106:107], v[46:47]
	s_waitcnt lgkmcnt(1)
	v_mfma_f32_16x16x32_bf16 v[2:5], v[14:17], v[10:13], v[2:5]
	ds_read_b128 v[10:13], v182 offset:256
	v_pk_mul_f32 v[44:45], v[104:105], v[44:45]
	v_pk_mul_f32 v[42:43], v[106:107], v[42:43]
	v_mfma_f32_16x16x32_bf16 v[6:9], v[18:21], v[22:25], v[6:9]
	v_mul_f32_e64 v40, v104, v40
	v_mul_f32_e64 v41, v105, v41
	v_pk_mul_f32 v[38:39], v[106:107], v[38:39]
	s_add_i32 s14, s14, s85
	s_waitcnt lgkmcnt(1)
	v_mfma_f32_16x16x32_bf16 v[2:5], v[18:21], v[26:29], v[2:5]
	ds_read_b128 v[14:17], v183 offset:34048
	ds_read_b128 v[18:21], v182 offset:320
	ds_read_b128 v[22:25], v183 offset:34112
	s_add_i32 s13, s13, s50
	s_add_i32 s12, s12, s85
	s_waitcnt lgkmcnt(2)
	v_mfma_f32_16x16x32_bf16 v[6:9], v[10:13], v[14:17], v[6:9]
	ds_read_b128 v[14:17], v183 offset:42496
	ds_read_b128 v[26:29], v183 offset:42560
	s_add_i32 s11, s11, s51
	s_waitcnt lgkmcnt(1)
	v_mfma_f32_16x16x32_bf16 v[2:5], v[10:13], v[14:17], v[2:5]
	ds_read_b128 v[10:13], v182 offset:384
	v_mfma_f32_16x16x32_bf16 v[6:9], v[18:21], v[22:25], v[6:9]
	s_waitcnt lgkmcnt(1)
	v_mfma_f32_16x16x32_bf16 v[2:5], v[18:21], v[26:29], v[2:5]
	ds_read_b128 v[14:17], v183 offset:34176
	ds_read_b128 v[18:21], v182 offset:448
	ds_read_b128 v[22:25], v183 offset:34240
	s_waitcnt lgkmcnt(2)
	v_mfma_f32_16x16x32_bf16 v[6:9], v[10:13], v[14:17], v[6:9]
	ds_read_b128 v[14:17], v183 offset:42624
	ds_read_b128 v[26:29], v183 offset:42688
	s_waitcnt lgkmcnt(1)
	v_mfma_f32_16x16x32_bf16 v[2:5], v[10:13], v[14:17], v[2:5]
	v_mfma_f32_16x16x32_bf16 v[6:9], v[18:21], v[22:25], v[6:9]
	s_waitcnt lgkmcnt(0)
	v_mfma_f32_16x16x32_bf16 v[2:5], v[18:21], v[26:29], v[2:5]
	s_nop 5
	v_mul_f32_e32 v1, v103, v6
	v_cvt_pk_bf16_f32 v1, v1, s0
	ds_write_b16 v74, v1
	v_mul_f32_e32 v1, v198, v2
	v_cvt_pk_bf16_f32 v1, v1, s0
	ds_write_b16 v205, v1
	v_mul_f32_e32 v1, v199, v7
	v_cvt_pk_bf16_f32 v1, v1, s0
	ds_write_b16 v75, v1
	v_mul_f32_e32 v1, v200, v3
	v_cvt_pk_bf16_f32 v1, v1, s0
	ds_write_b16 v206, v1
	v_mul_f32_e32 v1, v201, v8
	v_cvt_pk_bf16_f32 v1, v1, s0
	ds_write_b16 v76, v1
	v_mul_f32_e32 v1, v202, v4
	v_cvt_pk_bf16_f32 v1, v1, s0
	ds_write_b16 v207, v1
	v_mul_f32_e32 v1, v203, v9
	v_cvt_pk_bf16_f32 v1, v1, s0
	ds_write_b16 v77, v1
	v_mul_f32_e32 v1, v204, v5
	v_cvt_pk_bf16_f32 v1, v1, s0
	ds_write_b16 v208, v1
	s_waitcnt lgkmcnt(0)
	s_barrier
	ds_read_b128 v[2:5], v184
	ds_read_b128 v[6:9], v182
	ds_read_b128 v[10:13], v182 offset:64
	ds_read_b128 v[14:17], v184 offset:64
	s_waitcnt lgkmcnt(2)
	v_mfma_f32_16x16x32_bf16 v[2:5], v[2:5], v[6:9], 0
	ds_read_b128 v[18:21], v184 offset:8448
	ds_read_b128 v[22:25], v184 offset:8512
	s_waitcnt lgkmcnt(2)
	v_mfma_f32_16x16x32_bf16 v[2:5], v[14:17], v[10:13], v[2:5]
	ds_read_b128 v[14:17], v184 offset:128
	s_waitcnt lgkmcnt(2)
	v_mfma_f32_16x16x32_bf16 v[6:9], v[18:21], v[6:9], 0
	s_waitcnt lgkmcnt(1)
	v_mfma_f32_16x16x32_bf16 v[6:9], v[22:25], v[10:13], v[6:9]
	ds_read_b128 v[10:13], v182 offset:128
	ds_read_b128 v[18:21], v182 offset:192
	ds_read_b128 v[22:25], v184 offset:192
	s_waitcnt lgkmcnt(2)
	v_mfma_f32_16x16x32_bf16 v[2:5], v[14:17], v[10:13], v[2:5]
	ds_read_b128 v[14:17], v184 offset:8576
	ds_read_b128 v[26:29], v184 offset:8640
	s_waitcnt lgkmcnt(1)
	v_mfma_f32_16x16x32_bf16 v[6:9], v[14:17], v[10:13], v[6:9]
	ds_read_b128 v[10:13], v184 offset:256
	v_mfma_f32_16x16x32_bf16 v[2:5], v[22:25], v[18:21], v[2:5]
	s_waitcnt lgkmcnt(1)
	v_mfma_f32_16x16x32_bf16 v[6:9], v[26:29], v[18:21], v[6:9]
	ds_read_b128 v[14:17], v182 offset:256
	ds_read_b128 v[18:21], v182 offset:320
	ds_read_b128 v[22:25], v184 offset:320
	s_waitcnt lgkmcnt(2)
	v_mfma_f32_16x16x32_bf16 v[2:5], v[10:13], v[14:17], v[2:5]
	ds_read_b128 v[10:13], v184 offset:8704
	ds_read_b128 v[26:29], v184 offset:8768
	s_waitcnt lgkmcnt(1)
	v_mfma_f32_16x16x32_bf16 v[6:9], v[10:13], v[14:17], v[6:9]
	ds_read_b128 v[10:13], v184 offset:384
	v_mfma_f32_16x16x32_bf16 v[2:5], v[22:25], v[18:21], v[2:5]
	s_waitcnt lgkmcnt(1)
	v_mfma_f32_16x16x32_bf16 v[6:9], v[26:29], v[18:21], v[6:9]
	ds_read_b128 v[14:17], v182 offset:384
	ds_read_b128 v[18:21], v182 offset:448
	ds_read_b128 v[22:25], v184 offset:448
	s_waitcnt lgkmcnt(2)
	v_mfma_f32_16x16x32_bf16 v[2:5], v[10:13], v[14:17], v[2:5]
	ds_read_b128 v[10:13], v184 offset:8832
	ds_read_b128 v[26:29], v184 offset:8896
	s_waitcnt lgkmcnt(1)
	v_mfma_f32_16x16x32_bf16 v[6:9], v[10:13], v[14:17], v[6:9]
	ds_read_b128 v[10:13], v185
	v_mfma_f32_16x16x32_bf16 v[2:5], v[22:25], v[18:21], v[2:5]
	s_waitcnt lgkmcnt(1)
	v_mfma_f32_16x16x32_bf16 v[6:9], v[26:29], v[18:21], v[6:9]
	ds_read_b64_tr_b16 v[18:19], v141
	ds_read_b64_tr_b16 v[20:21], v142
	ds_read_b64_tr_b16 v[14:15], v143
	ds_read_b64_tr_b16 v[16:17], v144
	s_waitcnt lgkmcnt(0)
	s_nop 5
	v_mul_f32_e64 v4, v110, v4
	v_mul_f32_e64 v5, v111, v5
	v_pk_mul_f32 v[2:3], v[108:109], v[2:3]
	v_pk_mul_f32 v[28:29], v[106:107], v[58:59]
	s_waitcnt lgkmcnt(0)
	v_mfma_f32_16x16x32_bf16 v[2:5], v[18:21], v[10:13], v[2:5]
	v_mul_f32_e64 v8, v110, v8
	v_mul_f32_e64 v9, v111, v9
	v_pk_mul_f32 v[6:7], v[108:109], v[6:7]
	s_nop 1
	v_mfma_f32_16x16x32_bf16 v[6:9], v[14:17], v[10:13], v[6:9]
	ds_read_b128 v[10:13], v185 offset:64
	ds_read_b64_tr_b16 v[18:19], v145
	ds_read_b64_tr_b16 v[20:21], v146
	ds_read_b64_tr_b16 v[14:15], v147
	ds_read_b64_tr_b16 v[16:17], v148
	s_waitcnt lgkmcnt(0)
	s_waitcnt lgkmcnt(0)
	v_mfma_f32_16x16x32_bf16 v[2:5], v[18:21], v[10:13], v[2:5]
	v_lshl_add_u64 v[18:19], s[36:37], 0, v[186:187]
	s_or_b32 s36, s38, 0xfc0
	s_mov_b32 s37, s57
	v_mfma_f32_16x16x32_bf16 v[6:9], v[14:17], v[10:13], v[6:9]
	v_lshl_add_u64 v[10:11], v[80:81], 0, s[36:37]
	v_lshl_add_u64 v[18:19], v[18:19], 0, s[56:57]
	s_nop 1
	v_cvt_pk_bf16_f32 v2, v2, v3
	v_cvt_pk_bf16_f32 v3, v4, v5
	s_cmpk_lt_i32 s14, 0x100
	s_nop 0
	v_cvt_pk_bf16_f32 v4, v6, v7
	v_lshlrev_b64 v[6:7], 13, v[10:11]
	v_lshl_add_u64 v[6:7], v[18:19], 0, v[6:7]
	v_cvt_pk_bf16_f32 v5, v8, v9
	global_store_dwordx2 v[6:7], v[2:3], off
	global_store_dwordx2 v[6:7], v[4:5], off offset:32
	v_pk_mul_f32 v[4:5], v[104:105], v[68:69]
	v_pk_mul_f32 v[2:3], v[106:107], v[66:67]
	ds_read_b64_tr_b16 v[12:13], v149
	ds_read_b64_tr_b16 v[14:15], v151
	ds_read_b64_tr_b16 v[8:9], v152
	ds_read_b64_tr_b16 v[10:11], v153
	s_waitcnt lgkmcnt(0)
	v_pk_mul_f32 v[6:7], v[104:105], v[64:65]
	ds_read_b64_tr_b16 v[20:21], v150
	ds_read_b64_tr_b16 v[22:23], v154
	ds_read_b64_tr_b16 v[16:17], v155
	ds_read_b64_tr_b16 v[18:19], v156
	s_waitcnt lgkmcnt(0)
	ds_read_b64_tr_b16 v[58:59], v157
	ds_read_b64_tr_b16 v[60:61], v158
	ds_read_b64_tr_b16 v[32:33], v159
	ds_read_b64_tr_b16 v[34:35], v160
	s_waitcnt lgkmcnt(0)
	s_nop 0
	v_mfma_f32_16x16x32_bf16 v[24:27], v[12:15], v[20:23], v[2:5]
	s_nop 2
	v_mul_f32_e64 v4, v106, v62
	v_mul_f32_e64 v5, v107, v63
	v_mfma_f32_16x16x32_bf16 v[28:31], v[12:15], v[58:61], v[28:31]
	s_nop 0
	v_mfma_f32_16x16x32_bf16 v[2:5], v[12:15], v[16:19], v[4:7]
	v_mfma_f32_16x16x32_bf16 v[12:15], v[12:15], v[32:35], v[50:53]
	s_nop 2
	v_mul_f32_e64 v52, v104, v56
	v_mul_f32_e64 v53, v105, v57
	v_pk_mul_f32 v[50:51], v[106:107], v[54:55]
	v_mfma_f32_16x16x32_bf16 v[16:19], v[8:11], v[16:19], v[46:49]
	s_nop 0
	v_mfma_f32_16x16x32_bf16 v[20:23], v[8:11], v[20:23], v[50:53]
	v_mfma_f32_16x16x32_bf16 v[42:45], v[8:11], v[58:61], v[42:45]
	v_mfma_f32_16x16x32_bf16 v[6:9], v[8:11], v[32:35], v[38:41]
	ds_read_b64_tr_b16 v[36:37], v161
	ds_read_b64_tr_b16 v[38:39], v163
	ds_read_b64_tr_b16 v[32:33], v164
	ds_read_b64_tr_b16 v[34:35], v165
	s_waitcnt lgkmcnt(0)
	ds_read_b64_tr_b16 v[50:51], v162
	ds_read_b64_tr_b16 v[52:53], v166
	ds_read_b64_tr_b16 v[46:47], v167
	ds_read_b64_tr_b16 v[48:49], v168
	s_waitcnt lgkmcnt(0)
	ds_read_b64_tr_b16 v[58:59], v169
	ds_read_b64_tr_b16 v[60:61], v170
	ds_read_b64_tr_b16 v[54:55], v171
	ds_read_b64_tr_b16 v[56:57], v172
	s_waitcnt lgkmcnt(0)
	s_nop 0
	v_mfma_f32_16x16x32_bf16 v[2:5], v[36:39], v[46:49], v[2:5]
	s_barrier
	v_mfma_f32_16x16x32_bf16 v[28:31], v[36:39], v[58:61], v[28:31]
	v_mfma_f32_16x16x32_bf16 v[10:13], v[36:39], v[54:57], v[12:15]
	s_nop 4
	v_cvt_pk_bf16_f32 v2, v2, v3
	v_cvt_pk_bf16_f32 v3, v4, v5
	ds_write_b64 v196, v[2:3] offset:8448
	v_mfma_f32_16x16x32_bf16 v[20:23], v[32:35], v[50:53], v[20:23]
	v_cvt_pk_bf16_f32 v2, v28, v29
	v_cvt_pk_bf16_f32 v3, v30, v31
	ds_write_b64 v196, v[2:3] offset:16896
	v_mfma_f32_16x16x32_bf16 v[14:17], v[32:35], v[46:49], v[16:19]
	v_cvt_pk_bf16_f32 v2, v10, v11
	v_cvt_pk_bf16_f32 v3, v12, v13
	ds_write_b64 v196, v[2:3] offset:25344
	v_mfma_f32_16x16x32_bf16 v[24:27], v[36:39], v[50:53], v[24:27]
	v_cvt_pk_bf16_f32 v2, v20, v21
	v_cvt_pk_bf16_f32 v3, v22, v23
	ds_write_b64 v197, v[2:3]
	v_mfma_f32_16x16x32_bf16 v[36:39], v[32:35], v[58:61], v[42:45]
	v_cvt_pk_bf16_f32 v2, v14, v15
	v_cvt_pk_bf16_f32 v3, v16, v17
	ds_write_b64 v197, v[2:3] offset:8448
	v_mfma_f32_16x16x32_bf16 v[6:9], v[32:35], v[54:57], v[6:9]
	v_cvt_pk_bf16_f32 v18, v24, v25
	s_nop 2
	v_cvt_pk_bf16_f32 v2, v36, v37
	v_cvt_pk_bf16_f32 v3, v38, v39
	v_cvt_pk_bf16_f32 v19, v26, v27
	ds_write_b64 v197, v[2:3] offset:16896
	v_cvt_pk_bf16_f32 v2, v6, v7
	v_cvt_pk_bf16_f32 v3, v8, v9
	ds_write_b64 v196, v[18:19]
	ds_write_b64 v197, v[2:3] offset:25344
	s_waitcnt lgkmcnt(0)
	s_barrier
	s_cbranch_scc1 .LBB0_434
